# speedup vs baseline: 1.0180x; 1.0060x over previous
; __device__ __forceinline__ int v_rd_base(int lane) { return ((lane & 3) << 3) | (((lane >> 2) & 3) << 6) | (((lane >> 4) & 1) << 5) | (((lane >> 5) & 1) << 8); }
; __device__ __forceinline__ void attn_body256(const bf16_t* __restrict__ Qb, const bf16_t* __restrict__ Kh, const bf16_t* __restrict__ Vh,
;                                              bf16_t* Ob, int seq, unsigned char* lds, float lam, int MODE, bf16_t* Ab, const float* wsub) {
;     ...
;   unsigned koff[2], voff[4];
; #pragma unroll
;   for (int i = 0; i < 2; ++i) { const int o = i * 8192 + tid * 16; const int row = o >> 8; const int colB = (o & 255) ^ ((row & 7) << 4);
;     koff[i] = (unsigned)(row * LDK + (colB >> 1));
;     const int sub = o >> 9, kk = (sub >> 2) * 8 + ((o & 511) >> 6), c = (sub & 3) * 32 + (((o & 511) >> 1) & 31);
;     const int k = (kk & ~0xC) | ((kk & 4) << 1) | ((kk & 8) >> 1);
;     voff[i] = (unsigned)(k * LDK + c); voff[2 + i] = (unsigned)(k * LDK + 128 + c); }
;     ...
;   const int NT = seq / KVBLK;
;   A2_DMA(0, 0); A2_DMA(1, 1);
;   float m_reg = -1e30f, l_reg = 0; f32x16 o[8] = {}; bf16x8 qr[8];
;   const bf16_t* Qw = Qb + (long)(wid * QBLK + r32) * LDQ + hi * 8;
; #pragma unroll
;   for (int d0 = 0; d0 < 8; ++d0) qr[d0] = *reinterpret_cast<const bf16x8*>(Qw + d0 * 16);
;   const int vb0 = (int)(uintptr_t)lds + v_rd_base(lane);
;   asm volatile("s_waitcnt vmcnt(0)" ::: "memory"); __syncthreads();
; __global__ void __launch_bounds__(512, 2) fwd_megakernel(Params p) {
;     ...
;         for (int u2 = blockIdx.x * 2; u2 < 2048; u2 += (u2 & 1) ? (int)gridDim.x * 2 - 1 : 1) {
;           const int ul = u2 >> 1, pass = u2 & 1;
;           int u = ul;
;           if (gridDim.x == 256) { const int it = ul >> 8, bq = ul & 255; u = (it >> 1) * 512 + (bq & 7) * 64 + (bq >> 3) + 32 * (it & 1); }
;           int h, rows0, seqb, seq;
;           if (u < 512) { const int qb = u & 63; h = u >> 6; rows0 = qb * 256; seqb = 0; seq = 16384; }
;           else { const int u3 = u - 512, qb = u3 & 63; h = u3 >> 6; seqb = TP + (qb >> 3) * 2048; rows0 = seqb + (qb & 7) * 256; seq = 2048; }
;           const int n = 2 * h + pass;
;           att::attn_body256(R0 + (size_t)rows0 * DM + n * 128, R1 + (size_t)seqb * DM + n * 128, R2 + (size_t)seqb * DM + h * 256,
;                             Od + (size_t)rows0 * DM + h * 256, seq, smem, lam, pass, Abuf + (size_t)rows0 * DM + h * 256, p.in[14]);
.LBB0_669:
	s_and_b32 s2, s18, 1
	s_lshl_b64 s[10:11], s[62:63], 11
	s_lshl_b64 s[6:7], s[62:63], 12
	s_add_u32 s9, s96, s6
	s_addc_u32 s12, s97, s7
	s_lshl_b32 s16, s8, 8
	s_lshl_b32 s6, s2, 7
	s_or_b32 s6, s16, s6
	s_ashr_i32 s7, s6, 31
	s_lshl_b64 s[14:15], s[6:7], 1
	s_add_u32 s6, s9, s14
	s_addc_u32 s7, s12, s15
	s_lshl_b64 s[8:9], s[0:1], 1
	s_add_u32 s0, s60, s8
	s_addc_u32 s1, s53, s9
	s_add_u32 s12, s0, s14
	s_addc_u32 s13, s1, s15
	v_mov_b32 v16, v231
	v_lshrrev_b32_e32 v245, 7, v231
	v_lshlrev_b32_e32 v245, 3, v245
	v_bfe_u32 v244, v231, 1, 3
	v_add_u32_e32 v245, v245, v244
	v_lshlrev_b32_e32 v245, 11, v245
	v_bfe_u32 v244, v231, 4, 3
	v_lshl_add_u32 v245, v244, 4, v245
	v_and_b32_e32 v244, 1, v231
	v_lshl_add_u32 v245, v244, 3, v245
	v_lshrrev_b32_e32 v239, 4, v231
	v_and_b32_e32 v244, 15, v239
	v_and_b32_e32 v242, 15, v231
	v_xor_b32_e32 v242, v242, v244
	v_lshlrev_b32_e32 v242, 3, v242
	v_lshl_add_u32 v239, v239, 11, v242
	s_add_u32 s20, s61, s8
	v_lshlrev_b32_e32 v17, 4, v16
	v_add_u32_e32 v6, 0x2000, v17
	s_addc_u32 s21, s68, s9
	s_ashr_i32 s17, s16, 31
	v_ashrrev_i32_e32 v8, 8, v6
	s_lshl_b64 s[0:1], s[16:17], 1
	v_and_b32_e32 v3, 0xf0, v17
	v_lshlrev_b32_e32 v6, 4, v8
	s_movk_i32 s26, 0x70
	s_add_u32 s16, s20, s0
	v_lshrrev_b32_e32 v0, 1, v16
	v_ashrrev_i32_e32 v2, 4, v16
	v_bitop3_b32 v3, v6, v3, s26 bitop3:0x6c
	s_addc_u32 s17, s21, s1
	v_readfirstlane_b32 s20, v16
	v_and_b32_e32 v22, 8, v0
	v_and_b32_e32 v0, 0x70, v16
	s_movk_i32 s21, 0xf0
	v_lshrrev_b32_e32 v4, 1, v2
	v_lshrrev_b32_e32 v3, 1, v3
	s_ashr_i32 s23, s20, 6
	v_bfe_u32 v18, v16, 2, 2
	v_lshlrev_b32_e32 v20, 3, v16
	v_bitop3_b32 v0, v17, v0, s21 bitop3:0x6c
	v_and_b32_e32 v4, 4, v4
	v_lshl_or_b32 v6, v8, 11, v3
	v_add_u32_e32 v6, 0x10000, v239
	v_and_b32_e32 v3, 0x1ffff0, v8
	v_lshrrev_b32_e32 v8, 1, v8
	v_and_b32_e32 v19, 0x60, v16
	v_and_b32_e32 v21, 24, v20
	v_or_b32_e32 v7, v22, v18
	v_lshrrev_b32_e32 v0, 1, v0
	v_and_or_b32 v23, v2, -16, v4
	v_and_b32_e32 v8, 4, v8
	s_lshl_b32 s21, s23, 10
	v_or_b32_e32 v5, v21, v19
	v_lshl_or_b32 v0, v2, 11, v0
	v_mov_b32_e32 v0, v239
	v_or_b32_e32 v2, v7, v23
	v_or3_b32 v3, v3, v8, v7
	s_add_i32 s21, s21, 0
	v_lshl_or_b32 v2, v2, 11, v5
	v_mov_b32_e32 v2, v245
	v_lshlrev_b32_e32 v24, 11, v3
	s_add_i32 s22, s21, 0x10000
	v_lshlrev_b64 v[12:13], 1, v[0:1]
	v_mov_b32_e32 v3, v1
	v_or_b32_e32 v4, 0x80, v2
	v_lshl_add_u64 v[14:15], s[12:13], 0, v[12:13]
	s_mov_b32 m0, s22
	v_lshlrev_b64 v[2:3], 1, v[2:3]
	s_add_i32 s24, s21, 0x4000
	global_load_lds_dwordx4 v[14:15], off
	v_lshl_add_u64 v[14:15], s[16:17], 0, v[2:3]
	s_mov_b32 m0, s21
	s_mov_b64 s[30:31], 0x100
	v_mov_b32_e32 v7, v1
	s_and_b32 s20, s20, 0x3fffffc0
	v_or_b32_e32 v8, v24, v5
	v_add_u32_e32 v8, 0x10000, v245
	global_load_lds_dwordx4 v[14:15], off
	v_lshl_add_u64 v[14:15], v[14:15], 0, s[30:31]
	s_mov_b32 m0, s24
	v_lshlrev_b64 v[6:7], 1, v[6:7]
	v_mov_b32_e32 v9, v1
	s_lshl_b32 s20, s20, 2
	v_or_b32_e32 v10, 0x80, v8
	global_load_lds_dwordx4 v[14:15], off
	v_lshl_add_u64 v[14:15], s[12:13], 0, v[6:7]
	s_add_i32 m0, s21, 0x12000
	v_lshlrev_b64 v[8:9], 1, v[8:9]
	s_add_i32 s20, s20, 0
	global_load_lds_dwordx4 v[14:15], off
	v_lshl_add_u64 v[14:15], s[16:17], 0, v[8:9]
	s_add_i32 m0, s21, 0x2000
	s_add_i32 s20, s20, 0x18000
	global_load_lds_dwordx4 v[14:15], off
	s_add_i32 m0, s21, 0x6000
	s_add_u32 s12, s12, 0x40000
	s_addc_u32 s13, s13, 0
	v_lshl_add_u64 v[14:15], v[14:15], 0, s[30:31]
	s_add_u32 s16, s16, 0x40000
	global_load_lds_dwordx4 v[14:15], off
	s_addc_u32 s17, s17, 0
	s_add_i32 m0, s21, 0x14000
	s_add_i32 s24, s21, 0x8000
	v_lshl_add_u64 v[14:15], s[12:13], 0, v[12:13]
	v_mov_b32_e32 v5, v1
	s_add_i32 s25, s21, 0xc000
	global_load_lds_dwordx4 v[14:15], off
	v_lshl_add_u64 v[2:3], s[16:17], 0, v[2:3]
	s_mov_b32 m0, s24
	v_mov_b32_e32 v11, v1
	global_load_lds_dwordx4 v[2:3], off
	v_lshl_add_u64 v[2:3], v[4:5], 1, s[16:17]
	s_mov_b32 m0, s25
	v_and_b32_e32 v228, 31, v16
	global_load_lds_dwordx4 v[2:3], off
	v_lshl_add_u64 v[2:3], s[12:13], 0, v[6:7]
	s_add_i32 m0, s21, 0x16000
	s_lshl_b32 s12, s23, 5
	global_load_lds_dwordx4 v[2:3], off
	v_lshl_add_u64 v[2:3], s[16:17], 0, v[8:9]
	s_add_i32 m0, s21, 0xa000
	v_bfe_u32 v229, v16, 5, 1
	global_load_lds_dwordx4 v[2:3], off
	v_lshl_add_u64 v[2:3], v[10:11], 1, s[16:17]
	s_add_i32 m0, s21, 0xe000
	v_lshlrev_b32_e32 v0, 4, v229
	global_load_lds_dwordx4 v[2:3], off
	v_and_b32_e32 v2, 15, v231
	v_or_b32_e32 v2, s12, v2
	v_mov_b32_e32 v3, 0
	v_lshlrev_b64 v[2:3], 12, v[2:3]
	v_lshl_add_u64 v[2:3], s[6:7], 0, v[2:3]
	v_bfe_u32 v194, v231, 4, 2
	v_lshlrev_b32_e32 v194, 4, v194
	v_mov_b32_e32 v195, 0
	v_lshl_add_u64 v[2:3], v[2:3], 0, v[194:195]
	global_load_dwordx4 v[162:165], v[2:3], off
	global_load_dwordx4 v[166:169], v[2:3], off offset:64
	global_load_dwordx4 v[170:173], v[2:3], off offset:128
	global_load_dwordx4 v[174:177], v[2:3], off offset:192
	v_mov_b32_e32 v194, 0x10000
	v_lshl_add_u64 v[2:3], v[2:3], 0, v[194:195]
	global_load_dwordx4 v[178:181], v[2:3], off
	global_load_dwordx4 v[182:185], v[2:3], off offset:64
	global_load_dwordx4 v[186:189], v[2:3], off offset:128
	global_load_dwordx4 v[190:193], v[2:3], off offset:192
	v_and_b32_e32 v8, 0x70, v17
	s_movk_i32 s6, 0x60
	v_bitop3_b32 v236, v0, v8, s6 bitop3:0x36
	s_movk_i32 s6, 0x80
	v_bitop3_b32 v237, v0, v8, s6 bitop3:0x36
	s_movk_i32 s6, 0xa0
	v_bitop3_b32 v240, v0, v8, s6 bitop3:0x36
	s_movk_i32 s6, 0xc0
	s_cmp_lg_u32 0, -1
	v_and_b32_e32 v2, 63, v16
	v_lshlrev_b32_e32 v3, 1, v16
	v_and_b32_e32 v4, 0x118, v20
	v_bitop3_b32 v241, v0, v8, s6 bitop3:0x36
	s_movk_i32 s6, 0xe0
	s_cselect_b32 s16, 0, 0
	s_lshl_b32 s23, s19, 18
	v_and_b32_e32 v5, 0xc0, v17
	v_bitop3_b32 v247, v0, v8, s6 bitop3:0x36
	v_cmp_gt_u32_e64 s[6:7], 32, v2
	v_and_or_b32 v2, v3, 32, v4
	s_add_u32 s14, s8, s14
	v_add3_u32 v248, v5, s16, v2
	s_addc_u32 s15, s9, s15
	v_readlane_b32 s16, v254, 41
	s_add_u32 s14, s16, s14
	v_readlane_b32 s16, v254, 42
	s_addc_u32 s15, s16, s15
	s_add_u32 s8, s8, s0
	s_addc_u32 s9, s9, s1
	v_or3_b32 v2, v23, v22, v18
	v_lshlrev_b32_e32 v2, 11, v2
	s_add_u32 s8, s88, s8
	v_or3_b32 v2, v2, v19, v21
	v_mov_b32_e32 v2, v245
	v_mov_b32_e32 v3, v1
	s_addc_u32 s9, s89, s9
	s_waitcnt vmcnt(0)
; __device__ __forceinline__ int v_rd_base(int lane) { return ((lane & 3) << 3) | (((lane >> 2) & 3) << 6) | (((lane >> 4) & 1) << 5) | (((lane >> 5) & 1) << 8); }
; __device__ __forceinline__ void qkt(f32x16& p0, f32x16& p1, const bf16_t* Ks, const bf16x8* qr, int r32, int hi) {
;   p0 = f32x16{}; p1 = f32x16{};
;   for (int d0 = 0; d0 < 8; ++d0) { int cb = (d0 * 16 + hi * 8) * 2;
;     bf16x8 b0 = *reinterpret_cast<const bf16x8*>((const char*)Ks + KSWZ(r32, cb));
;     bf16x8 b1 = *reinterpret_cast<const bf16x8*>((const char*)Ks + KSWZ(32 + r32, cb));
; __device__ __forceinline__ void attn_body256(const bf16_t* __restrict__ Qb, const bf16_t* __restrict__ Kh, const bf16_t* __restrict__ Vh,
;                                              bf16_t* Ob, int seq, unsigned char* lds, float lam, int MODE, bf16_t* Ab, const float* wsub) {
;     ...
;   float m_reg = -1e30f, l_reg = 0; f32x16 o[8] = {}; bf16x8 qr[8];
;   const bf16_t* Qw = Qb + (long)(wid * QBLK + r32) * LDQ + hi * 8;
; #pragma unroll
;   for (int d0 = 0; d0 < 8; ++d0) qr[d0] = *reinterpret_cast<const bf16x8*>(Qw + d0 * 16);
;   const int vb0 = (int)(uintptr_t)lds + v_rd_base(lane);
;   asm volatile("s_waitcnt vmcnt(0)" ::: "memory"); __syncthreads();
	v_bitop3_b32 v232, v0, v17, s26 bitop3:0x78
	v_lshl_add_u64 v[224:225], v[2:3], 1, s[8:9]
	v_or3_b32 v2, v24, v19, v21
	v_add_u32_e32 v2, 0x10000, v245
	v_mov_b32_e32 v16, v1
	v_mov_b32_e32 v17, v1
	v_bitop3_b32 v233, v0, v8, 32 bitop3:0x36
	v_bitop3_b32 v234, v0, v8, 64 bitop3:0x36
	v_lshl_add_u64 v[220:221], s[14:15], 0, v[12:13]
	v_lshl_add_u64 v[222:223], s[14:15], 0, v[6:7]
	v_lshl_add_u64 v[226:227], v[2:3], 1, s[8:9]
	v_mov_b32_e32 v2, v1
	v_mov_b32_e32 v4, v1
	v_mov_b32_e32 v5, v1
	v_mov_b32_e32 v6, v1
	v_mov_b32_e32 v7, v1
	v_mov_b32_e32 v8, v1
	v_mov_b32_e32 v9, v1
	v_mov_b32_e32 v10, v1
	v_mov_b32_e32 v12, v1
	v_mov_b32_e32 v13, v1
	v_mov_b32_e32 v14, v1
	v_mov_b32_e32 v15, v1
	v_mov_b64_e32 v[128:129], v[16:17]
	v_mov_b64_e32 v[112:113], v[16:17]
	v_mov_b64_e32 v[96:97], v[16:17]
	v_mov_b64_e32 v[80:81], v[16:17]
	v_mov_b64_e32 v[64:65], v[16:17]
	v_mov_b64_e32 v[48:49], v[16:17]
	v_mov_b64_e32 v[32:33], v[16:17]
	s_mov_b32 s13, 2
	v_lshlrev_b32_e32 v230, 8, v228
	v_lshl_add_u32 v238, v228, 2, s20
	v_mov_b32_e32 v250, 0
	v_mov_b32_e32 v249, 0xf149f2ca
	s_mov_b64 s[14:15], 0
	v_mov_b64_e32 v[126:127], v[14:15]
	v_mov_b64_e32 v[124:125], v[12:13]
	v_mov_b64_e32 v[122:123], v[10:11]
	v_mov_b64_e32 v[120:121], v[8:9]
	v_mov_b64_e32 v[118:119], v[6:7]
	v_mov_b64_e32 v[116:117], v[4:5]
	v_mov_b64_e32 v[114:115], v[2:3]
	v_mov_b64_e32 v[110:111], v[14:15]
	v_mov_b64_e32 v[108:109], v[12:13]
	v_mov_b64_e32 v[106:107], v[10:11]
	v_mov_b64_e32 v[104:105], v[8:9]
	v_mov_b64_e32 v[102:103], v[6:7]
	v_mov_b64_e32 v[100:101], v[4:5]
	v_mov_b64_e32 v[98:99], v[2:3]
	v_mov_b64_e32 v[94:95], v[14:15]
	v_mov_b64_e32 v[92:93], v[12:13]
	v_mov_b64_e32 v[90:91], v[10:11]
	v_mov_b64_e32 v[88:89], v[8:9]
	v_mov_b64_e32 v[86:87], v[6:7]
	v_mov_b64_e32 v[84:85], v[4:5]
	v_mov_b64_e32 v[82:83], v[2:3]
	v_mov_b64_e32 v[78:79], v[14:15]
	v_mov_b64_e32 v[76:77], v[12:13]
	v_mov_b64_e32 v[74:75], v[10:11]
	v_mov_b64_e32 v[72:73], v[8:9]
	v_mov_b64_e32 v[70:71], v[6:7]
	v_mov_b64_e32 v[68:69], v[4:5]
	v_mov_b64_e32 v[66:67], v[2:3]
	v_mov_b64_e32 v[62:63], v[14:15]
	v_mov_b64_e32 v[60:61], v[12:13]
	v_mov_b64_e32 v[58:59], v[10:11]
	v_mov_b64_e32 v[56:57], v[8:9]
	v_mov_b64_e32 v[54:55], v[6:7]
	v_mov_b64_e32 v[52:53], v[4:5]
	v_mov_b64_e32 v[50:51], v[2:3]
	v_mov_b64_e32 v[46:47], v[14:15]
	v_mov_b64_e32 v[44:45], v[12:13]
	v_mov_b64_e32 v[42:43], v[10:11]
	v_mov_b64_e32 v[40:41], v[8:9]
	v_mov_b64_e32 v[38:39], v[6:7]
	v_mov_b64_e32 v[36:37], v[4:5]
	v_mov_b64_e32 v[34:35], v[2:3]
	v_mov_b64_e32 v[30:31], v[14:15]
	v_mov_b64_e32 v[28:29], v[12:13]
	v_mov_b64_e32 v[26:27], v[10:11]
	v_mov_b64_e32 v[24:25], v[8:9]
	v_mov_b64_e32 v[22:23], v[6:7]
	v_mov_b64_e32 v[20:21], v[4:5]
	v_mov_b64_e32 v[18:19], v[2:3]
	v_and_b32_e32 v237, 15, v231
	v_bfe_u32 v240, v231, 4, 2
	v_add_u32_e32 v247, 0, v240
	v_xor_b32_e32 v247, v247, v237
	v_lshlrev_b32_e32 v247, 4, v247
	v_lshl_add_u32 v232, v237, 8, v247
	v_add_u32_e32 v247, 4, v240
	v_xor_b32_e32 v247, v247, v237
	v_lshlrev_b32_e32 v247, 4, v247
	v_lshl_add_u32 v233, v237, 8, v247
	v_add_u32_e32 v247, 8, v240
	v_xor_b32_e32 v247, v247, v237
	v_lshlrev_b32_e32 v247, 4, v247
	v_lshl_add_u32 v242, v237, 8, v247
	v_add_u32_e32 v247, 12, v240
	v_xor_b32_e32 v247, v247, v237
	v_lshlrev_b32_e32 v247, 4, v247
	v_lshl_add_u32 v243, v237, 8, v247
	v_and_b32_e32 v247, 1, v240
	v_lshlrev_b32_e32 v248, 7, v247
	v_lshrrev_b32_e32 v247, 1, v240
	v_lshl_add_u32 v248, v247, 11, v248
	v_bfe_u32 v247, v231, 2, 2
	v_lshl_add_u32 v248, v247, 5, v248
	v_and_b32_e32 v247, 3, v231
	v_lshl_add_u32 v248, v247, 3, v248
	v_mov_b32_e32 v249, 0xf149f2ca
	v_mov_b32_e32 v246, 0xf149f2ca
	v_mov_b32_e32 v250, 0
	v_mov_b32_e32 v234, 0
	s_movk_i32 s62, 0x7fff
	s_waitcnt vmcnt(0) lgkmcnt(0)
	s_barrier
	s_mov_b32 s98, 0
	s_mov_b32 s99, 0x8000
	s_mov_b32 s100, 0x19000
	s_cmpk_ge_u32 s21, 0x1000
	s_cbranch_scc1 .Lat_y_qk
	s_mov_b32 s9, 0x10000
	v_add_u32_e32 v230, s9, v232
	v_add_u32_e32 v247, s9, v233
	v_add_u32_e32 v239, s9, v242
	v_add_u32_e32 v245, s9, v243
	ds_read_b128 v[194:197], v230
	ds_read_b128 v[198:201], v230 offset:4096
	ds_read_b128 v[202:205], v230 offset:8192
	ds_read_b128 v[206:209], v230 offset:12288
	ds_read_b128 v[210:213], v247
	ds_read_b128 v[214:217], v247 offset:4096
; __device__ __forceinline__ void partialSM(f32x16& p0, f32x16& p1, float& m_reg, float& mn, float& alpha) {
;   constexpr float C = SCALE * 1.4426950408889634f;
;   float pmax = p0[0]; for (int r = 1; r < 16; ++r) pmax = fmaxf(pmax, p0[r]); for (int r = 0; r < 16; ++r) pmax = fmaxf(pmax, p1[r]);
;   { auto rr = __builtin_amdgcn_permlane32_swap(__float_as_uint(pmax), __float_as_uint(pmax), false, false);
;     pmax = fmaxf(__uint_as_float(rr[0]), __uint_as_float(rr[1])); }
;   if (__builtin_expect(__all(pmax - m_reg <= THR / SCALE), 1)) { mn = m_reg; alpha = 1.f; }
;   else { mn = fmaxf(m_reg, pmax); alpha = __builtin_amdgcn_exp2f((m_reg - mn) * C); m_reg = mn; }
;   float mnC = -mn * C;
;   for (int r = 0; r < 16; ++r) p0[r] = fmaf(p0[r], C, mnC); for (int r = 0; r < 16; ++r) p1[r] = fmaf(p1[r], C, mnC);
;   for (int r = 0; r < 16; ++r) p0[r] = __builtin_amdgcn_exp2f(p0[r]);
; }
; __device__ __forceinline__ void qkt(f32x16& p0, f32x16& p1, const bf16_t* Ks, const bf16x8* qr, int r32, int hi) {
;   p0 = f32x16{}; p1 = f32x16{};
;   for (int d0 = 0; d0 < 8; ++d0) { int cb = (d0 * 16 + hi * 8) * 2;
;     bf16x8 b0 = *reinterpret_cast<const bf16x8*>((const char*)Ks + KSWZ(r32, cb));
;     bf16x8 b1 = *reinterpret_cast<const bf16x8*>((const char*)Ks + KSWZ(32 + r32, cb));
;     p0 = __builtin_amdgcn_mfma_f32_32x32x16_bf16(b0, qr[d0], p0, 0, 0, 0);
;     p1 = __builtin_amdgcn_mfma_f32_32x32x16_bf16(b1, qr[d0], p1, 0, 0, 0); }
; }
.Lat_x_top:
	s_add_i32 s8, s13, -2
	s_and_b32 s25, s8, 1
	s_lshl_b32 s24, s25, 14
	s_setprio 1
	s_waitcnt lgkmcnt(5)
	v_mfma_f32_16x16x32_bf16 v[130:133], v[194:197], v[162:165], 0
	v_mfma_f32_16x16x32_bf16 v[134:137], v[194:197], v[178:181], 0
	ds_read_b128 v[194:197], v247 offset:8192
	s_waitcnt lgkmcnt(5)
	v_mfma_f32_16x16x32_bf16 v[138:141], v[198:201], v[162:165], 0
	v_mfma_f32_16x16x32_bf16 v[142:145], v[198:201], v[178:181], 0
	ds_read_b128 v[198:201], v247 offset:12288
	s_waitcnt lgkmcnt(5)
	v_mfma_f32_16x16x32_bf16 v[146:149], v[202:205], v[162:165], 0
	v_mfma_f32_16x16x32_bf16 v[150:153], v[202:205], v[178:181], 0
	ds_read_b128 v[202:205], v239
	s_waitcnt lgkmcnt(5)
	v_mfma_f32_16x16x32_bf16 v[154:157], v[206:209], v[162:165], 0
	v_mfma_f32_16x16x32_bf16 v[158:161], v[206:209], v[178:181], 0
	ds_read_b128 v[206:209], v239 offset:4096
	s_waitcnt lgkmcnt(5)
	v_mfma_f32_16x16x32_bf16 v[130:133], v[210:213], v[166:169], v[130:133]
	v_mfma_f32_16x16x32_bf16 v[134:137], v[210:213], v[182:185], v[134:137]
	ds_read_b128 v[210:213], v239 offset:8192
	s_waitcnt lgkmcnt(5)
	v_mfma_f32_16x16x32_bf16 v[138:141], v[214:217], v[166:169], v[138:141]
	v_mfma_f32_16x16x32_bf16 v[142:145], v[214:217], v[182:185], v[142:145]
	ds_read_b128 v[214:217], v239 offset:12288
	s_waitcnt lgkmcnt(5)
	v_mfma_f32_16x16x32_bf16 v[146:149], v[194:197], v[166:169], v[146:149]
	v_mfma_f32_16x16x32_bf16 v[150:153], v[194:197], v[182:185], v[150:153]
	ds_read_b128 v[194:197], v245
	s_waitcnt lgkmcnt(5)
	v_mfma_f32_16x16x32_bf16 v[154:157], v[198:201], v[166:169], v[154:157]
	v_mfma_f32_16x16x32_bf16 v[158:161], v[198:201], v[182:185], v[158:161]
	ds_read_b128 v[198:201], v245 offset:4096
	s_waitcnt lgkmcnt(5)
	v_mfma_f32_16x16x32_bf16 v[130:133], v[202:205], v[170:173], v[130:133]
	v_mfma_f32_16x16x32_bf16 v[134:137], v[202:205], v[186:189], v[134:137]
	ds_read_b128 v[202:205], v245 offset:8192
	s_waitcnt lgkmcnt(5)
	v_mfma_f32_16x16x32_bf16 v[138:141], v[206:209], v[170:173], v[138:141]
	v_mfma_f32_16x16x32_bf16 v[142:145], v[206:209], v[186:189], v[142:145]
	ds_read_b128 v[206:209], v245 offset:12288
	s_waitcnt lgkmcnt(5)
	v_mfma_f32_16x16x32_bf16 v[146:149], v[210:213], v[170:173], v[146:149]
	v_mfma_f32_16x16x32_bf16 v[150:153], v[210:213], v[186:189], v[150:153]
	s_waitcnt lgkmcnt(4)
	v_mfma_f32_16x16x32_bf16 v[154:157], v[214:217], v[170:173], v[154:157]
	v_mfma_f32_16x16x32_bf16 v[158:161], v[214:217], v[186:189], v[158:161]
	s_waitcnt lgkmcnt(3)
	v_mfma_f32_16x16x32_bf16 v[130:133], v[194:197], v[174:177], v[130:133]
	v_mfma_f32_16x16x32_bf16 v[134:137], v[194:197], v[190:193], v[134:137]
	s_waitcnt lgkmcnt(2)
	v_mfma_f32_16x16x32_bf16 v[138:141], v[198:201], v[174:177], v[138:141]
	v_mfma_f32_16x16x32_bf16 v[142:145], v[198:201], v[190:193], v[142:145]
	s_waitcnt lgkmcnt(1)
	v_mfma_f32_16x16x32_bf16 v[146:149], v[202:205], v[174:177], v[146:149]
	v_mfma_f32_16x16x32_bf16 v[150:153], v[202:205], v[190:193], v[150:153]
	s_waitcnt lgkmcnt(0)
	v_mfma_f32_16x16x32_bf16 v[154:157], v[206:209], v[174:177], v[154:157]
	v_mfma_f32_16x16x32_bf16 v[158:161], v[206:209], v[190:193], v[158:161]
	s_setprio 0
	s_nop 6
	v_max3_f32 v194, v130, v131, v132
	v_max3_f32 v194, v194, v133, v138
	v_max3_f32 v194, v194, v139, v140
	v_max3_f32 v194, v194, v141, v146
	v_max3_f32 v194, v194, v147, v148
	v_max3_f32 v194, v194, v149, v154
	v_max3_f32 v194, v194, v155, v156
	v_max_f32_e32 v194, v194, v157
	v_max3_f32 v195, v134, v135, v136
	v_max3_f32 v195, v195, v137, v142
	v_max3_f32 v195, v195, v143, v144
	v_max3_f32 v195, v195, v145, v150
	v_max3_f32 v195, v195, v151, v152
	v_max3_f32 v195, v195, v153, v158
	v_max3_f32 v195, v195, v159, v160
	v_max_f32_e32 v195, v195, v161
	v_mov_b32_e32 v196, v194
	v_mov_b32_e32 v197, v195
	s_nop 1
	v_permlane32_swap_b32_e32 v194, v196
	v_permlane32_swap_b32_e32 v195, v197
	v_max_f32_e32 v194, v194, v196
	v_max_f32_e32 v195, v195, v197
	v_mov_b32_e32 v196, v194
	v_mov_b32_e32 v197, v195
	s_nop 1
	v_permlane16_swap_b32_e32 v194, v196
	v_permlane16_swap_b32_e32 v195, v197
	v_max_f32_e32 v194, v194, v196
	v_max_f32_e32 v195, v195, v197
	v_sub_f32_e32 v196, v194, v249
	v_sub_f32_e32 v197, v195, v246
	v_max_f32_e32 v196, v196, v197
	v_cmp_ge_f32_e32 vcc, 0x42b504f3, v196
	v_max_f32_e32 v198, v249, v194
	v_max_f32_e32 v199, v246, v195
	v_sub_f32_e32 v196, v249, v198
	v_sub_f32_e32 v197, v246, v199
	v_mul_f32_e32 v196, 0x3e0293ee, v196
	v_mul_f32_e32 v197, 0x3e0293ee, v197
	v_exp_f32_e32 v196, v196
	v_exp_f32_e32 v197, v197
	s_cmp_eq_u64 vcc, exec
	s_cselect_b64 s[8:9], -1, 0
	v_cndmask_b32_e64 v236, v196, 1.0, s[8:9]
	v_cndmask_b32_e64 v240, v197, 1.0, s[8:9]
	v_cndmask_b32_e64 v249, v198, v249, s[8:9]
	v_cndmask_b32_e64 v246, v199, v246, s[8:9]
	s_cbranch_scc1 .Lat_x_noresc
; __device__ __forceinline__ int crow(int r, int hi) { return (r & 3) + 8 * (r >> 2) + 4 * hi; }
; __device__ __forceinline__ int crow(int r, int hi) { return (r & 3) + 8 * (r >> 2) + 4 * hi; }
; __device__ __forceinline__ void partialSM(f32x16& p0, f32x16& p1, float& m_reg, float& mn, float& alpha) {
;     ...
;   float mnC = -mn * C;
;   for (int r = 0; r < 16; ++r) p0[r] = fmaf(p0[r], C, mnC); for (int r = 0; r < 16; ++r) p1[r] = fmaf(p1[r], C, mnC);
;   for (int r = 0; r < 16; ++r) p0[r] = __builtin_amdgcn_exp2f(p0[r]);
; __device__ __forceinline__ void attn_body256(const bf16_t* __restrict__ Qb, const bf16_t* __restrict__ Kh, const bf16_t* __restrict__ Vh,
;                                              bf16_t* Ob, int seq, unsigned char* lds, float lam, int MODE, bf16_t* Ab, const float* wsub) {
;     ...
;     if (__any(alpha < 1.f)) { if (hi == 0) al_l[r32] = alpha; asm volatile("s_waitcnt lgkmcnt(0)" ::: "memory");
; #pragma unroll
;       for (int r = 0; r < 16; ++r) { const float a = al_l[crow(r, hi)];
; #pragma unroll
;         for (int d = 0; d < 8; ++d) o[d][r] *= a; } }
	v_pk_mul_f32 v[2:3], v[2:3], v[236:237] op_sel_hi:[1,0]
	v_pk_mul_f32 v[4:5], v[4:5], v[236:237] op_sel_hi:[1,0]
	v_pk_mul_f32 v[6:7], v[6:7], v[240:241] op_sel_hi:[1,0]
	v_pk_mul_f32 v[8:9], v[8:9], v[240:241] op_sel_hi:[1,0]
	v_pk_mul_f32 v[10:11], v[10:11], v[236:237] op_sel_hi:[1,0]
	v_pk_mul_f32 v[12:13], v[12:13], v[236:237] op_sel_hi:[1,0]
	v_pk_mul_f32 v[14:15], v[14:15], v[240:241] op_sel_hi:[1,0]
	v_pk_mul_f32 v[16:17], v[16:17], v[240:241] op_sel_hi:[1,0]
	v_pk_mul_f32 v[114:115], v[114:115], v[236:237] op_sel_hi:[1,0]
	v_pk_mul_f32 v[116:117], v[116:117], v[236:237] op_sel_hi:[1,0]
	v_pk_mul_f32 v[118:119], v[118:119], v[240:241] op_sel_hi:[1,0]
	v_pk_mul_f32 v[120:121], v[120:121], v[240:241] op_sel_hi:[1,0]
	v_pk_mul_f32 v[122:123], v[122:123], v[236:237] op_sel_hi:[1,0]
	v_pk_mul_f32 v[124:125], v[124:125], v[236:237] op_sel_hi:[1,0]
	v_pk_mul_f32 v[126:127], v[126:127], v[240:241] op_sel_hi:[1,0]
	v_pk_mul_f32 v[128:129], v[128:129], v[240:241] op_sel_hi:[1,0]
	v_pk_mul_f32 v[98:99], v[98:99], v[236:237] op_sel_hi:[1,0]
	v_pk_mul_f32 v[100:101], v[100:101], v[236:237] op_sel_hi:[1,0]
	v_pk_mul_f32 v[102:103], v[102:103], v[240:241] op_sel_hi:[1,0]
	v_pk_mul_f32 v[104:105], v[104:105], v[240:241] op_sel_hi:[1,0]
	v_pk_mul_f32 v[106:107], v[106:107], v[236:237] op_sel_hi:[1,0]
	v_pk_mul_f32 v[108:109], v[108:109], v[236:237] op_sel_hi:[1,0]
	v_pk_mul_f32 v[110:111], v[110:111], v[240:241] op_sel_hi:[1,0]
	v_pk_mul_f32 v[112:113], v[112:113], v[240:241] op_sel_hi:[1,0]
	v_pk_mul_f32 v[82:83], v[82:83], v[236:237] op_sel_hi:[1,0]
	v_pk_mul_f32 v[84:85], v[84:85], v[236:237] op_sel_hi:[1,0]
	v_pk_mul_f32 v[86:87], v[86:87], v[240:241] op_sel_hi:[1,0]
	v_pk_mul_f32 v[88:89], v[88:89], v[240:241] op_sel_hi:[1,0]
	v_pk_mul_f32 v[90:91], v[90:91], v[236:237] op_sel_hi:[1,0]
	v_pk_mul_f32 v[92:93], v[92:93], v[236:237] op_sel_hi:[1,0]
	v_pk_mul_f32 v[94:95], v[94:95], v[240:241] op_sel_hi:[1,0]
	v_pk_mul_f32 v[96:97], v[96:97], v[240:241] op_sel_hi:[1,0]
	v_pk_mul_f32 v[66:67], v[66:67], v[236:237] op_sel_hi:[1,0]
	v_pk_mul_f32 v[68:69], v[68:69], v[236:237] op_sel_hi:[1,0]
	v_pk_mul_f32 v[70:71], v[70:71], v[240:241] op_sel_hi:[1,0]
	v_pk_mul_f32 v[72:73], v[72:73], v[240:241] op_sel_hi:[1,0]
	v_pk_mul_f32 v[74:75], v[74:75], v[236:237] op_sel_hi:[1,0]
	v_pk_mul_f32 v[76:77], v[76:77], v[236:237] op_sel_hi:[1,0]
	v_pk_mul_f32 v[78:79], v[78:79], v[240:241] op_sel_hi:[1,0]
	v_pk_mul_f32 v[80:81], v[80:81], v[240:241] op_sel_hi:[1,0]
	v_pk_mul_f32 v[50:51], v[50:51], v[236:237] op_sel_hi:[1,0]
	v_pk_mul_f32 v[52:53], v[52:53], v[236:237] op_sel_hi:[1,0]
	v_pk_mul_f32 v[54:55], v[54:55], v[240:241] op_sel_hi:[1,0]
	v_pk_mul_f32 v[56:57], v[56:57], v[240:241] op_sel_hi:[1,0]
	v_pk_mul_f32 v[58:59], v[58:59], v[236:237] op_sel_hi:[1,0]
	v_pk_mul_f32 v[60:61], v[60:61], v[236:237] op_sel_hi:[1,0]
	v_pk_mul_f32 v[62:63], v[62:63], v[240:241] op_sel_hi:[1,0]
	v_pk_mul_f32 v[64:65], v[64:65], v[240:241] op_sel_hi:[1,0]
	v_pk_mul_f32 v[34:35], v[34:35], v[236:237] op_sel_hi:[1,0]
	v_pk_mul_f32 v[36:37], v[36:37], v[236:237] op_sel_hi:[1,0]
	v_pk_mul_f32 v[38:39], v[38:39], v[240:241] op_sel_hi:[1,0]
	v_pk_mul_f32 v[40:41], v[40:41], v[240:241] op_sel_hi:[1,0]
	v_pk_mul_f32 v[42:43], v[42:43], v[236:237] op_sel_hi:[1,0]
	v_pk_mul_f32 v[44:45], v[44:45], v[236:237] op_sel_hi:[1,0]
	v_pk_mul_f32 v[46:47], v[46:47], v[240:241] op_sel_hi:[1,0]
	v_pk_mul_f32 v[48:49], v[48:49], v[240:241] op_sel_hi:[1,0]
	v_pk_mul_f32 v[18:19], v[18:19], v[236:237] op_sel_hi:[1,0]
	v_pk_mul_f32 v[20:21], v[20:21], v[236:237] op_sel_hi:[1,0]
	v_pk_mul_f32 v[22:23], v[22:23], v[240:241] op_sel_hi:[1,0]
	v_pk_mul_f32 v[24:25], v[24:25], v[240:241] op_sel_hi:[1,0]
	v_pk_mul_f32 v[26:27], v[26:27], v[236:237] op_sel_hi:[1,0]
	v_pk_mul_f32 v[28:29], v[28:29], v[236:237] op_sel_hi:[1,0]
	v_pk_mul_f32 v[30:31], v[30:31], v[240:241] op_sel_hi:[1,0]
	v_pk_mul_f32 v[32:33], v[32:33], v[240:241] op_sel_hi:[1,0]
.Lat_x_noresc:
	v_mul_f32_e32 v198, 0xbe0293ee, v249
	v_mul_f32_e32 v199, 0xbe0293ee, v246
	v_fmamk_f32 v130, v130, 0x3e0293ee, v198
	v_fmamk_f32 v131, v131, 0x3e0293ee, v198
	v_fmamk_f32 v132, v132, 0x3e0293ee, v198
	v_fmamk_f32 v133, v133, 0x3e0293ee, v198
	v_fmamk_f32 v134, v134, 0x3e0293ee, v199
	v_fmamk_f32 v135, v135, 0x3e0293ee, v199
	v_fmamk_f32 v136, v136, 0x3e0293ee, v199
	v_fmamk_f32 v137, v137, 0x3e0293ee, v199
	v_fmamk_f32 v138, v138, 0x3e0293ee, v198
	v_fmamk_f32 v139, v139, 0x3e0293ee, v198
	v_fmamk_f32 v140, v140, 0x3e0293ee, v198
	v_fmamk_f32 v141, v141, 0x3e0293ee, v198
	v_fmamk_f32 v142, v142, 0x3e0293ee, v199
	v_fmamk_f32 v143, v143, 0x3e0293ee, v199
	v_fmamk_f32 v144, v144, 0x3e0293ee, v199
	v_fmamk_f32 v145, v145, 0x3e0293ee, v199
	v_fmamk_f32 v146, v146, 0x3e0293ee, v198
	v_fmamk_f32 v147, v147, 0x3e0293ee, v198
	v_fmamk_f32 v148, v148, 0x3e0293ee, v198
	v_fmamk_f32 v149, v149, 0x3e0293ee, v198
	v_fmamk_f32 v150, v150, 0x3e0293ee, v199
	v_fmamk_f32 v151, v151, 0x3e0293ee, v199
	v_fmamk_f32 v152, v152, 0x3e0293ee, v199
	v_fmamk_f32 v153, v153, 0x3e0293ee, v199
	v_fmamk_f32 v154, v154, 0x3e0293ee, v198
	v_fmamk_f32 v155, v155, 0x3e0293ee, v198
	v_fmamk_f32 v156, v156, 0x3e0293ee, v198
	v_fmamk_f32 v157, v157, 0x3e0293ee, v198
	v_fmamk_f32 v158, v158, 0x3e0293ee, v199
	v_fmamk_f32 v159, v159, 0x3e0293ee, v199
	v_fmamk_f32 v160, v160, 0x3e0293ee, v199
	v_fmamk_f32 v161, v161, 0x3e0293ee, v199
	v_exp_f32_e32 v130, v130
	v_exp_f32_e32 v131, v131
	v_exp_f32_e32 v132, v132
	v_exp_f32_e32 v133, v133
	v_exp_f32_e32 v134, v134
	v_exp_f32_e32 v135, v135
	v_exp_f32_e32 v136, v136
	v_exp_f32_e32 v137, v137
	v_exp_f32_e32 v138, v138
	v_exp_f32_e32 v139, v139
; #define SBAR() __builtin_amdgcn_sched_barrier(0)
; #define PV_STEP(B) do { pv_reads<(B) + 1>(fn, vb); asm volatile("s_waitcnt lgkmcnt(8)" ::: "memory"); SBAR(); pv_mma(o[B], fc, pa0, pa1, pa2, pa3); SBAR(); fc = fn; } while (0)
; __device__ __forceinline__ void partialSM(f32x16& p0, f32x16& p1, float& m_reg, float& mn, float& alpha) {
;     ...
;   for (int r = 0; r < 16; ++r) p0[r] = __builtin_amdgcn_exp2f(p0[r]);
; }
; __device__ __forceinline__ void finishSM(f32x16& p0, f32x16& p1, float alpha, float& l_reg, bf16x8& pa0, bf16x8& pa1, bf16x8& pa2, bf16x8& pa3) {
;   for (int r = 0; r < 16; ++r) p1[r] = __builtin_amdgcn_exp2f(p1[r]);
;   float ps = 0; for (int r = 0; r < 16; ++r) ps += p0[r]; for (int r = 0; r < 16; ++r) ps += p1[r];
;   { auto rr = __builtin_amdgcn_permlane32_swap(__float_as_uint(ps), __float_as_uint(ps), false, false);
;     ps = __uint_as_float(rr[0]) + __uint_as_float(rr[1]); }
;   l_reg = l_reg * alpha + ps;
;     ...
;   PK4(p0, 0, pa0); PK4(p0, 8, pa1); PK4(p1, 0, pa2); PK4(p1, 8, pa3);
; template <int B> __device__ __forceinline__ void pv_reads(VFrag& f, int vb) {
;   constexpr int base = (B >> 2) * 16384 + (B & 3) * 512;
;   f.l0 = tr_read<base + 0 * 4096>(vb); f.h0 = tr_read<base + 0 * 4096 + 2048>(vb); f.l1 = tr_read<base + 1 * 4096>(vb); f.h1 = tr_read<base + 1 * 4096 + 2048>(vb);
;   f.l2 = tr_read<base + 2 * 4096>(vb); f.h2 = tr_read<base + 2 * 4096 + 2048>(vb); f.l3 = tr_read<base + 3 * 4096>(vb); f.h3 = tr_read<base + 3 * 4096 + 2048>(vb);
; }
; __device__ __forceinline__ void pv_mma(f32x16& od, const VFrag& f, bf16x8 pa0, bf16x8 pa1, bf16x8 pa2, bf16x8 pa3) {
;     ...
;   od = __builtin_amdgcn_mfma_f32_32x32x16_bf16(pa0, PKV(f.l0, f.h0), od, 0, 0, 0);
;   od = __builtin_amdgcn_mfma_f32_32x32x16_bf16(pa1, PKV(f.l1, f.h1), od, 0, 0, 0);
;   od = __builtin_amdgcn_mfma_f32_32x32x16_bf16(pa2, PKV(f.l2, f.h2), od, 0, 0, 0);
;   od = __builtin_amdgcn_mfma_f32_32x32x16_bf16(pa3, PKV(f.l3, f.h3), od, 0, 0, 0);
;     ...
; }
; __device__ __forceinline__ void pv_all(f32x16* o, int vb, bf16x8 pa0, bf16x8 pa1, bf16x8 pa2, bf16x8 pa3) {
;   VFrag fc, fn;
;   pv_reads<0>(fc, vb);
;   PV_STEP(0); PV_STEP(1); PV_STEP(2); PV_STEP(3); PV_STEP(4); PV_STEP(5); PV_STEP(6);
;   asm volatile("s_waitcnt lgkmcnt(0)" ::: "memory"); SBAR(); pv_mma(o[7], fc, pa0, pa1, pa2, pa3);
; }
	v_exp_f32_e32 v140, v140
	v_exp_f32_e32 v141, v141
	v_exp_f32_e32 v142, v142
	v_exp_f32_e32 v143, v143
	v_exp_f32_e32 v144, v144
	v_exp_f32_e32 v145, v145
	v_exp_f32_e32 v146, v146
	v_exp_f32_e32 v147, v147
	v_exp_f32_e32 v148, v148
	v_exp_f32_e32 v149, v149
	v_exp_f32_e32 v150, v150
	v_exp_f32_e32 v151, v151
	v_exp_f32_e32 v152, v152
	v_exp_f32_e32 v153, v153
	v_exp_f32_e32 v154, v154
	v_exp_f32_e32 v155, v155
	v_exp_f32_e32 v156, v156
	v_exp_f32_e32 v157, v157
	v_exp_f32_e32 v158, v158
	v_exp_f32_e32 v159, v159
	v_exp_f32_e32 v160, v160
	v_exp_f32_e32 v161, v161
	v_add_f32_e32 v194, v130, v131
	v_add_f32_e32 v194, v194, v132
	v_add_f32_e32 v194, v194, v133
	v_add_f32_e32 v194, v194, v138
	v_add_f32_e32 v194, v194, v139
	v_add_f32_e32 v194, v194, v140
	v_add_f32_e32 v194, v194, v141
	v_add_f32_e32 v194, v194, v146
	v_add_f32_e32 v194, v194, v147
	v_add_f32_e32 v194, v194, v148
	v_add_f32_e32 v194, v194, v149
	v_add_f32_e32 v194, v194, v154
	v_add_f32_e32 v194, v194, v155
	v_add_f32_e32 v194, v194, v156
	v_add_f32_e32 v194, v194, v157
	v_add_f32_e32 v195, v134, v135
	v_add_f32_e32 v195, v195, v136
	v_add_f32_e32 v195, v195, v137
	v_add_f32_e32 v195, v195, v142
	v_add_f32_e32 v195, v195, v143
	v_add_f32_e32 v195, v195, v144
	v_add_f32_e32 v195, v195, v145
	v_add_f32_e32 v195, v195, v150
	v_add_f32_e32 v195, v195, v151
	v_add_f32_e32 v195, v195, v152
	v_add_f32_e32 v195, v195, v153
	v_add_f32_e32 v195, v195, v158
	v_add_f32_e32 v195, v195, v159
	v_add_f32_e32 v195, v195, v160
	v_add_f32_e32 v195, v195, v161
	v_fma_f32 v250, v250, v236, v194
	v_fma_f32 v234, v234, v240, v195
	v_cvt_pk_bf16_f32 v130, v130, v131
	v_cvt_pk_bf16_f32 v131, v132, v133
	v_cvt_pk_bf16_f32 v132, v138, v139
	v_cvt_pk_bf16_f32 v133, v140, v141
	v_cvt_pk_bf16_f32 v134, v134, v135
	v_cvt_pk_bf16_f32 v135, v136, v137
	v_cvt_pk_bf16_f32 v136, v142, v143
	v_cvt_pk_bf16_f32 v137, v144, v145
	v_cvt_pk_bf16_f32 v138, v146, v147
	v_cvt_pk_bf16_f32 v139, v148, v149
	v_cvt_pk_bf16_f32 v140, v154, v155
	v_cvt_pk_bf16_f32 v141, v156, v157
	v_cvt_pk_bf16_f32 v142, v150, v151
	v_cvt_pk_bf16_f32 v143, v152, v153
	v_cvt_pk_bf16_f32 v144, v158, v159
	v_cvt_pk_bf16_f32 v145, v160, v161
	v_add_u32_e32 v244, s98, v248
	ds_read_b64_tr_b16 v[146:147], v244
	ds_read_b64_tr_b16 v[148:149], v244 offset:4096
	ds_read_b64_tr_b16 v[150:151], v244 offset:8192
	ds_read_b64_tr_b16 v[152:153], v244 offset:12288
	ds_read_b64_tr_b16 v[154:155], v244 offset:256
	ds_read_b64_tr_b16 v[156:157], v244 offset:4352
	ds_read_b64_tr_b16 v[158:159], v244 offset:8448
	ds_read_b64_tr_b16 v[160:161], v244 offset:12544
	ds_read_b64_tr_b16 v[194:195], v244 offset:512
	ds_read_b64_tr_b16 v[196:197], v244 offset:4608
	ds_read_b64_tr_b16 v[198:199], v244 offset:8704
	ds_read_b64_tr_b16 v[200:201], v244 offset:12800
	s_waitcnt lgkmcnt(8)
	v_mfma_f32_16x16x32_bf16 v[2:5], v[146:149], v[130:133], v[2:5]
	v_mfma_f32_16x16x32_bf16 v[6:9], v[146:149], v[134:137], v[6:9]
	v_mfma_f32_16x16x32_bf16 v[2:5], v[150:153], v[138:141], v[2:5]
	v_mfma_f32_16x16x32_bf16 v[6:9], v[150:153], v[142:145], v[6:9]
	ds_read_b64_tr_b16 v[146:147], v244 offset:768
	ds_read_b64_tr_b16 v[148:149], v244 offset:4864
	ds_read_b64_tr_b16 v[150:151], v244 offset:8960
	ds_read_b64_tr_b16 v[152:153], v244 offset:13056
	s_waitcnt lgkmcnt(8)
	v_mfma_f32_16x16x32_bf16 v[10:13], v[154:157], v[130:133], v[10:13]
	v_mfma_f32_16x16x32_bf16 v[14:17], v[154:157], v[134:137], v[14:17]
	v_mfma_f32_16x16x32_bf16 v[10:13], v[158:161], v[138:141], v[10:13]
	v_mfma_f32_16x16x32_bf16 v[14:17], v[158:161], v[142:145], v[14:17]
	ds_read_b64_tr_b16 v[154:155], v244 offset:1024
	ds_read_b64_tr_b16 v[156:157], v244 offset:5120
	ds_read_b64_tr_b16 v[158:159], v244 offset:9216
	ds_read_b64_tr_b16 v[160:161], v244 offset:13312
	s_waitcnt lgkmcnt(8)
	v_mfma_f32_16x16x32_bf16 v[114:117], v[194:197], v[130:133], v[114:117]
	v_mfma_f32_16x16x32_bf16 v[118:121], v[194:197], v[134:137], v[118:121]
	v_mfma_f32_16x16x32_bf16 v[114:117], v[198:201], v[138:141], v[114:117]
	v_mfma_f32_16x16x32_bf16 v[118:121], v[198:201], v[142:145], v[118:121]
	ds_read_b64_tr_b16 v[194:195], v244 offset:1280
	ds_read_b64_tr_b16 v[196:197], v244 offset:5376
	ds_read_b64_tr_b16 v[198:199], v244 offset:9472
	ds_read_b64_tr_b16 v[200:201], v244 offset:13568
	s_waitcnt lgkmcnt(8)
	v_mfma_f32_16x16x32_bf16 v[122:125], v[146:149], v[130:133], v[122:125]
	v_mfma_f32_16x16x32_bf16 v[126:129], v[146:149], v[134:137], v[126:129]
	v_mfma_f32_16x16x32_bf16 v[122:125], v[150:153], v[138:141], v[122:125]
	v_mfma_f32_16x16x32_bf16 v[126:129], v[150:153], v[142:145], v[126:129]
	ds_read_b64_tr_b16 v[146:147], v244 offset:1536
	ds_read_b64_tr_b16 v[148:149], v244 offset:5632
	ds_read_b64_tr_b16 v[150:151], v244 offset:9728
	ds_read_b64_tr_b16 v[152:153], v244 offset:13824
	s_waitcnt lgkmcnt(8)
	v_mfma_f32_16x16x32_bf16 v[98:101], v[154:157], v[130:133], v[98:101]
	v_mfma_f32_16x16x32_bf16 v[102:105], v[154:157], v[134:137], v[102:105]
	v_mfma_f32_16x16x32_bf16 v[98:101], v[158:161], v[138:141], v[98:101]
	v_mfma_f32_16x16x32_bf16 v[102:105], v[158:161], v[142:145], v[102:105]
	ds_read_b64_tr_b16 v[154:155], v244 offset:1792
	ds_read_b64_tr_b16 v[156:157], v244 offset:5888
	ds_read_b64_tr_b16 v[158:159], v244 offset:9984
	ds_read_b64_tr_b16 v[160:161], v244 offset:14080
	s_waitcnt lgkmcnt(8)
	v_mfma_f32_16x16x32_bf16 v[106:109], v[194:197], v[130:133], v[106:109]
	v_mfma_f32_16x16x32_bf16 v[110:113], v[194:197], v[134:137], v[110:113]
	v_mfma_f32_16x16x32_bf16 v[106:109], v[198:201], v[138:141], v[106:109]
	v_mfma_f32_16x16x32_bf16 v[110:113], v[198:201], v[142:145], v[110:113]
	ds_read_b64_tr_b16 v[194:195], v244 offset:16384
	ds_read_b64_tr_b16 v[196:197], v244 offset:20480
	ds_read_b64_tr_b16 v[198:199], v244 offset:24576
	ds_read_b64_tr_b16 v[200:201], v244 offset:28672
	s_waitcnt lgkmcnt(8)
; template <int B> __device__ __forceinline__ void pv_reads(VFrag& f, int vb) {
;   constexpr int base = (B >> 2) * 16384 + (B & 3) * 512;
;   f.l0 = tr_read<base + 0 * 4096>(vb); f.h0 = tr_read<base + 0 * 4096 + 2048>(vb); f.l1 = tr_read<base + 1 * 4096>(vb); f.h1 = tr_read<base + 1 * 4096 + 2048>(vb);
;   f.l2 = tr_read<base + 2 * 4096>(vb); f.h2 = tr_read<base + 2 * 4096 + 2048>(vb); f.l3 = tr_read<base + 3 * 4096>(vb); f.h3 = tr_read<base + 3 * 4096 + 2048>(vb);
; }
; __device__ __forceinline__ void pv_mma(f32x16& od, const VFrag& f, bf16x8 pa0, bf16x8 pa1, bf16x8 pa2, bf16x8 pa3) {
;     ...
;   od = __builtin_amdgcn_mfma_f32_32x32x16_bf16(pa0, PKV(f.l0, f.h0), od, 0, 0, 0);
;   od = __builtin_amdgcn_mfma_f32_32x32x16_bf16(pa1, PKV(f.l1, f.h1), od, 0, 0, 0);
;   od = __builtin_amdgcn_mfma_f32_32x32x16_bf16(pa2, PKV(f.l2, f.h2), od, 0, 0, 0);
;   od = __builtin_amdgcn_mfma_f32_32x32x16_bf16(pa3, PKV(f.l3, f.h3), od, 0, 0, 0);
;     ...
; }
; __device__ __forceinline__ void pv_all(f32x16* o, int vb, bf16x8 pa0, bf16x8 pa1, bf16x8 pa2, bf16x8 pa3) {
;   VFrag fc, fn;
;   pv_reads<0>(fc, vb);
;   PV_STEP(0); PV_STEP(1); PV_STEP(2); PV_STEP(3); PV_STEP(4); PV_STEP(5); PV_STEP(6);
;   asm volatile("s_waitcnt lgkmcnt(0)" ::: "memory"); SBAR(); pv_mma(o[7], fc, pa0, pa1, pa2, pa3);
; }
; __device__ __forceinline__ void attn_body256(const bf16_t* __restrict__ Qb, const bf16_t* __restrict__ Kh, const bf16_t* __restrict__ Vh,
;                                              bf16_t* Ob, int seq, unsigned char* lds, float lam, int MODE, bf16_t* Ab, const float* wsub) {
;     ...
;   const int NT = seq / KVBLK;
;   A2_DMA(0, 0); A2_DMA(1, 1);
;   float m_reg = -1e30f, l_reg = 0; f32x16 o[8] = {}; bf16x8 qr[8];
;   const bf16_t* Qw = Qb + (long)(wid * QBLK + r32) * LDQ + hi * 8;
; #pragma unroll
;   for (int d0 = 0; d0 < 8; ++d0) qr[d0] = *reinterpret_cast<const bf16x8*>(Qw + d0 * 16);
;   const int vb0 = (int)(uintptr_t)lds + v_rd_base(lane);
;   asm volatile("s_waitcnt vmcnt(0)" ::: "memory"); __syncthreads();
;   for (int j = 0; j < NT; ++j) {
;     const int b = j & 1;
;     f32x16 p0, p1; float mn, alpha; bf16x8 pa0, pa1, pa2, pa3;
;     SBAR(); qkt(p0, p1, (const bf16_t*)(lds + A2_KOFF + b * A2_KBUF), qr, r32, hi);
;     partialSM(p0, p1, m_reg, mn, alpha);
;     if (__any(alpha < 1.f)) { if (hi == 0) al_l[r32] = alpha; asm volatile("s_waitcnt lgkmcnt(0)" ::: "memory");
; #pragma unroll
	v_mfma_f32_16x16x32_bf16 v[82:85], v[146:149], v[130:133], v[82:85]
	v_mfma_f32_16x16x32_bf16 v[86:89], v[146:149], v[134:137], v[86:89]
	v_mfma_f32_16x16x32_bf16 v[82:85], v[150:153], v[138:141], v[82:85]
	v_mfma_f32_16x16x32_bf16 v[86:89], v[150:153], v[142:145], v[86:89]
	ds_read_b64_tr_b16 v[146:147], v244 offset:16640
	ds_read_b64_tr_b16 v[148:149], v244 offset:20736
	ds_read_b64_tr_b16 v[150:151], v244 offset:24832
	ds_read_b64_tr_b16 v[152:153], v244 offset:28928
	s_waitcnt lgkmcnt(8)
	v_mfma_f32_16x16x32_bf16 v[90:93], v[154:157], v[130:133], v[90:93]
	v_mfma_f32_16x16x32_bf16 v[94:97], v[154:157], v[134:137], v[94:97]
	v_mfma_f32_16x16x32_bf16 v[90:93], v[158:161], v[138:141], v[90:93]
	v_mfma_f32_16x16x32_bf16 v[94:97], v[158:161], v[142:145], v[94:97]
	ds_read_b64_tr_b16 v[154:155], v244 offset:16896
	ds_read_b64_tr_b16 v[156:157], v244 offset:20992
	ds_read_b64_tr_b16 v[158:159], v244 offset:25088
	ds_read_b64_tr_b16 v[160:161], v244 offset:29184
	s_waitcnt lgkmcnt(8)
	v_mfma_f32_16x16x32_bf16 v[66:69], v[194:197], v[130:133], v[66:69]
	v_mfma_f32_16x16x32_bf16 v[70:73], v[194:197], v[134:137], v[70:73]
	v_mfma_f32_16x16x32_bf16 v[66:69], v[198:201], v[138:141], v[66:69]
	v_mfma_f32_16x16x32_bf16 v[70:73], v[198:201], v[142:145], v[70:73]
	ds_read_b64_tr_b16 v[194:195], v244 offset:17152
	ds_read_b64_tr_b16 v[196:197], v244 offset:21248
	ds_read_b64_tr_b16 v[198:199], v244 offset:25344
	ds_read_b64_tr_b16 v[200:201], v244 offset:29440
	s_waitcnt lgkmcnt(8)
	v_mfma_f32_16x16x32_bf16 v[74:77], v[146:149], v[130:133], v[74:77]
	v_mfma_f32_16x16x32_bf16 v[78:81], v[146:149], v[134:137], v[78:81]
	v_mfma_f32_16x16x32_bf16 v[74:77], v[150:153], v[138:141], v[74:77]
	v_mfma_f32_16x16x32_bf16 v[78:81], v[150:153], v[142:145], v[78:81]
	ds_read_b64_tr_b16 v[146:147], v244 offset:17408
	ds_read_b64_tr_b16 v[148:149], v244 offset:21504
	ds_read_b64_tr_b16 v[150:151], v244 offset:25600
	ds_read_b64_tr_b16 v[152:153], v244 offset:29696
	s_waitcnt lgkmcnt(8)
	v_mfma_f32_16x16x32_bf16 v[50:53], v[154:157], v[130:133], v[50:53]
	v_mfma_f32_16x16x32_bf16 v[54:57], v[154:157], v[134:137], v[54:57]
	v_mfma_f32_16x16x32_bf16 v[50:53], v[158:161], v[138:141], v[50:53]
	v_mfma_f32_16x16x32_bf16 v[54:57], v[158:161], v[142:145], v[54:57]
	ds_read_b64_tr_b16 v[154:155], v244 offset:17664
	ds_read_b64_tr_b16 v[156:157], v244 offset:21760
	ds_read_b64_tr_b16 v[158:159], v244 offset:25856
	ds_read_b64_tr_b16 v[160:161], v244 offset:29952
	s_waitcnt lgkmcnt(8)
	v_mfma_f32_16x16x32_bf16 v[58:61], v[194:197], v[130:133], v[58:61]
	v_mfma_f32_16x16x32_bf16 v[62:65], v[194:197], v[134:137], v[62:65]
	v_mfma_f32_16x16x32_bf16 v[58:61], v[198:201], v[138:141], v[58:61]
	v_mfma_f32_16x16x32_bf16 v[62:65], v[198:201], v[142:145], v[62:65]
	ds_read_b64_tr_b16 v[194:195], v244 offset:17920
	ds_read_b64_tr_b16 v[196:197], v244 offset:22016
	ds_read_b64_tr_b16 v[198:199], v244 offset:26112
	ds_read_b64_tr_b16 v[200:201], v244 offset:30208
	s_waitcnt lgkmcnt(8)
	v_mfma_f32_16x16x32_bf16 v[34:37], v[146:149], v[130:133], v[34:37]
	v_mfma_f32_16x16x32_bf16 v[38:41], v[146:149], v[134:137], v[38:41]
	v_mfma_f32_16x16x32_bf16 v[34:37], v[150:153], v[138:141], v[34:37]
	v_mfma_f32_16x16x32_bf16 v[38:41], v[150:153], v[142:145], v[38:41]
	ds_read_b64_tr_b16 v[146:147], v244 offset:18176
	ds_read_b64_tr_b16 v[148:149], v244 offset:22272
	ds_read_b64_tr_b16 v[150:151], v244 offset:26368
	ds_read_b64_tr_b16 v[152:153], v244 offset:30464
	s_waitcnt lgkmcnt(8)
	v_mfma_f32_16x16x32_bf16 v[42:45], v[154:157], v[130:133], v[42:45]
	v_mfma_f32_16x16x32_bf16 v[46:49], v[154:157], v[134:137], v[46:49]
	v_mfma_f32_16x16x32_bf16 v[42:45], v[158:161], v[138:141], v[42:45]
	v_mfma_f32_16x16x32_bf16 v[46:49], v[158:161], v[142:145], v[46:49]
	s_waitcnt lgkmcnt(4)
	v_mfma_f32_16x16x32_bf16 v[18:21], v[194:197], v[130:133], v[18:21]
	v_mfma_f32_16x16x32_bf16 v[22:25], v[194:197], v[134:137], v[22:25]
	v_mfma_f32_16x16x32_bf16 v[18:21], v[198:201], v[138:141], v[18:21]
	v_mfma_f32_16x16x32_bf16 v[22:25], v[198:201], v[142:145], v[22:25]
	s_waitcnt lgkmcnt(0)
	v_mfma_f32_16x16x32_bf16 v[26:29], v[146:149], v[130:133], v[26:29]
	v_mfma_f32_16x16x32_bf16 v[30:33], v[146:149], v[134:137], v[30:33]
	v_mfma_f32_16x16x32_bf16 v[26:29], v[150:153], v[138:141], v[26:29]
	v_mfma_f32_16x16x32_bf16 v[30:33], v[150:153], v[142:145], v[30:33]
	s_waitcnt vmcnt(0)
	s_barrier
	s_xor_b32 s9, s25, 1
	s_lshl_b32 s9, s9, 14
	s_add_i32 s9, s9, 0x10000
	v_add_u32_e32 v230, s9, v232
	v_add_u32_e32 v247, s9, v233
	v_add_u32_e32 v239, s9, v242
	v_add_u32_e32 v245, s9, v243
	ds_read_b128 v[194:197], v230
	ds_read_b128 v[198:201], v230 offset:4096
	ds_read_b128 v[202:205], v230 offset:8192
	ds_read_b128 v[206:209], v230 offset:12288
	ds_read_b128 v[210:213], v247
	ds_read_b128 v[214:217], v247 offset:4096
	s_cmp_ge_u32 s13, s19
	s_cbranch_scc1 .Lat_x_nodma
	v_lshl_add_u64 v[130:131], v[220:221], 0, s[14:15]
	v_lshl_add_u64 v[132:133], v[222:223], 0, s[14:15]
	v_lshl_add_u64 v[134:135], v[224:225], 0, s[14:15]
	v_lshl_add_u64 v[136:137], v[226:227], 0, s[14:15]
	v_lshl_add_u64 v[138:139], v[134:135], 0, s[54:55]
	v_lshl_add_u64 v[134:135], v[134:135], 0, s[4:5]
	v_lshl_add_u64 v[140:141], v[136:137], 0, s[54:55]
	v_lshl_add_u64 v[136:137], v[136:137], 0, s[4:5]
	s_add_i32 s9, s22, s24
	s_add_i32 s8, s21, s100
	s_mov_b32 m0, s9
	s_nop 0
	global_load_lds_dwordx4 v[130:131], off
	s_add_i32 m0, s9, 0x2000
	s_nop 0
	global_load_lds_dwordx4 v[132:133], off
	s_mov_b32 m0, s8
	s_nop 0
	global_load_lds_dwordx4 v[138:139], off
	s_add_i32 m0, s8, 0x4000
	s_nop 0
	global_load_lds_dwordx4 v[134:135], off
	s_add_i32 m0, s8, 0x2000
	s_nop 0
	global_load_lds_dwordx4 v[140:141], off
	s_add_i32 m0, s8, 0x6000
	s_nop 0
	global_load_lds_dwordx4 v[136:137], off

; __device__ __forceinline__ void partialSM(f32x16& p0, f32x16& p1, float& m_reg, float& mn, float& alpha) {
;   constexpr float C = SCALE * 1.4426950408889634f;
;   float pmax = p0[0]; for (int r = 1; r < 16; ++r) pmax = fmaxf(pmax, p0[r]); for (int r = 0; r < 16; ++r) pmax = fmaxf(pmax, p1[r]);
;   { auto rr = __builtin_amdgcn_permlane32_swap(__float_as_uint(pmax), __float_as_uint(pmax), false, false);
;     pmax = fmaxf(__uint_as_float(rr[0]), __uint_as_float(rr[1])); }
;   if (__builtin_expect(__all(pmax - m_reg <= THR / SCALE), 1)) { mn = m_reg; alpha = 1.f; }
;   else { mn = fmaxf(m_reg, pmax); alpha = __builtin_amdgcn_exp2f((m_reg - mn) * C); m_reg = mn; }
; __device__ __forceinline__ void qkt(f32x16& p0, f32x16& p1, const bf16_t* Ks, const bf16x8* qr, int r32, int hi) {
;   p0 = f32x16{}; p1 = f32x16{};
;   for (int d0 = 0; d0 < 8; ++d0) { int cb = (d0 * 16 + hi * 8) * 2;
;     bf16x8 b0 = *reinterpret_cast<const bf16x8*>((const char*)Ks + KSWZ(r32, cb));
;     bf16x8 b1 = *reinterpret_cast<const bf16x8*>((const char*)Ks + KSWZ(32 + r32, cb));
;     p0 = __builtin_amdgcn_mfma_f32_32x32x16_bf16(b0, qr[d0], p0, 0, 0, 0);
;     p1 = __builtin_amdgcn_mfma_f32_32x32x16_bf16(b1, qr[d0], p1, 0, 0, 0); }
.Lat_y_nodma:
.Lat_y_qk:
	s_add_i32 s8, s13, -2
	s_and_b32 s25, s8, 1
	s_lshl_b32 s24, s25, 14
	s_add_i32 s8, s24, 0x10000
	v_add_u32_e32 v230, s8, v232
	v_add_u32_e32 v247, s8, v233
	v_add_u32_e32 v239, s8, v242
	v_add_u32_e32 v245, s8, v243
	s_setprio 1
	ds_read_b128 v[194:197], v230
	ds_read_b128 v[198:201], v230 offset:4096
	ds_read_b128 v[202:205], v230 offset:8192
	ds_read_b128 v[206:209], v230 offset:12288
	ds_read_b128 v[210:213], v247
	ds_read_b128 v[214:217], v247 offset:4096
	s_waitcnt lgkmcnt(5)
	v_mfma_f32_16x16x32_bf16 v[130:133], v[194:197], v[162:165], 0
	v_mfma_f32_16x16x32_bf16 v[134:137], v[194:197], v[178:181], 0
	ds_read_b128 v[194:197], v247 offset:8192
	s_waitcnt lgkmcnt(5)
	v_mfma_f32_16x16x32_bf16 v[138:141], v[198:201], v[162:165], 0
	v_mfma_f32_16x16x32_bf16 v[142:145], v[198:201], v[178:181], 0
	ds_read_b128 v[198:201], v247 offset:12288
	s_waitcnt lgkmcnt(5)
	v_mfma_f32_16x16x32_bf16 v[146:149], v[202:205], v[162:165], 0
	v_mfma_f32_16x16x32_bf16 v[150:153], v[202:205], v[178:181], 0
	ds_read_b128 v[202:205], v239
	s_waitcnt lgkmcnt(5)
	v_mfma_f32_16x16x32_bf16 v[154:157], v[206:209], v[162:165], 0
	v_mfma_f32_16x16x32_bf16 v[158:161], v[206:209], v[178:181], 0
	ds_read_b128 v[206:209], v239 offset:4096
	s_waitcnt lgkmcnt(5)
	v_mfma_f32_16x16x32_bf16 v[130:133], v[210:213], v[166:169], v[130:133]
	v_mfma_f32_16x16x32_bf16 v[134:137], v[210:213], v[182:185], v[134:137]
	ds_read_b128 v[210:213], v239 offset:8192
	s_waitcnt lgkmcnt(5)
	v_mfma_f32_16x16x32_bf16 v[138:141], v[214:217], v[166:169], v[138:141]
	v_mfma_f32_16x16x32_bf16 v[142:145], v[214:217], v[182:185], v[142:145]
	ds_read_b128 v[214:217], v239 offset:12288
	s_waitcnt lgkmcnt(5)
	v_mfma_f32_16x16x32_bf16 v[146:149], v[194:197], v[166:169], v[146:149]
	v_mfma_f32_16x16x32_bf16 v[150:153], v[194:197], v[182:185], v[150:153]
	ds_read_b128 v[194:197], v245
	s_waitcnt lgkmcnt(5)
	v_mfma_f32_16x16x32_bf16 v[154:157], v[198:201], v[166:169], v[154:157]
	v_mfma_f32_16x16x32_bf16 v[158:161], v[198:201], v[182:185], v[158:161]
	ds_read_b128 v[198:201], v245 offset:4096
	s_waitcnt lgkmcnt(5)
	v_mfma_f32_16x16x32_bf16 v[130:133], v[202:205], v[170:173], v[130:133]
	v_mfma_f32_16x16x32_bf16 v[134:137], v[202:205], v[186:189], v[134:137]
	ds_read_b128 v[202:205], v245 offset:8192
	s_waitcnt lgkmcnt(5)
	v_mfma_f32_16x16x32_bf16 v[138:141], v[206:209], v[170:173], v[138:141]
	v_mfma_f32_16x16x32_bf16 v[142:145], v[206:209], v[186:189], v[142:145]
	ds_read_b128 v[206:209], v245 offset:12288
	s_waitcnt lgkmcnt(5)
	v_mfma_f32_16x16x32_bf16 v[146:149], v[210:213], v[170:173], v[146:149]
	v_mfma_f32_16x16x32_bf16 v[150:153], v[210:213], v[186:189], v[150:153]
	s_waitcnt lgkmcnt(4)
	v_mfma_f32_16x16x32_bf16 v[154:157], v[214:217], v[170:173], v[154:157]
	v_mfma_f32_16x16x32_bf16 v[158:161], v[214:217], v[186:189], v[158:161]
	s_waitcnt lgkmcnt(3)
	v_mfma_f32_16x16x32_bf16 v[130:133], v[194:197], v[174:177], v[130:133]
	v_mfma_f32_16x16x32_bf16 v[134:137], v[194:197], v[190:193], v[134:137]
	s_waitcnt lgkmcnt(2)
	v_mfma_f32_16x16x32_bf16 v[138:141], v[198:201], v[174:177], v[138:141]
	v_mfma_f32_16x16x32_bf16 v[142:145], v[198:201], v[190:193], v[142:145]
	s_waitcnt lgkmcnt(1)
	v_mfma_f32_16x16x32_bf16 v[146:149], v[202:205], v[174:177], v[146:149]
	v_mfma_f32_16x16x32_bf16 v[150:153], v[202:205], v[190:193], v[150:153]
	s_waitcnt lgkmcnt(0)
	v_mfma_f32_16x16x32_bf16 v[154:157], v[206:209], v[174:177], v[154:157]
	v_mfma_f32_16x16x32_bf16 v[158:161], v[206:209], v[190:193], v[158:161]
	s_setprio 0
	s_nop 6
	v_max3_f32 v194, v130, v131, v132
	v_max3_f32 v194, v194, v133, v138
	v_max3_f32 v194, v194, v139, v140
	v_max3_f32 v194, v194, v141, v146
	v_max3_f32 v194, v194, v147, v148
	v_max3_f32 v194, v194, v149, v154
	v_max3_f32 v194, v194, v155, v156
	v_max_f32_e32 v194, v194, v157
	v_max3_f32 v195, v134, v135, v136
	v_max3_f32 v195, v195, v137, v142
	v_max3_f32 v195, v195, v143, v144
	v_max3_f32 v195, v195, v145, v150
	v_max3_f32 v195, v195, v151, v152
	v_max3_f32 v195, v195, v153, v158
	v_max3_f32 v195, v195, v159, v160
	v_max_f32_e32 v195, v195, v161
	v_mov_b32_e32 v196, v194
	v_mov_b32_e32 v197, v195
	s_nop 1
	v_permlane32_swap_b32_e32 v194, v196
	v_permlane32_swap_b32_e32 v195, v197
	v_max_f32_e32 v194, v194, v196
	v_max_f32_e32 v195, v195, v197
	v_mov_b32_e32 v196, v194
	v_mov_b32_e32 v197, v195
	s_nop 1
	v_permlane16_swap_b32_e32 v194, v196
	v_permlane16_swap_b32_e32 v195, v197
	v_max_f32_e32 v194, v194, v196
	v_max_f32_e32 v195, v195, v197
	v_sub_f32_e32 v196, v194, v249
	v_sub_f32_e32 v197, v195, v246
	v_max_f32_e32 v196, v196, v197
	v_cmp_ge_f32_e32 vcc, 0x42b504f3, v196
	v_max_f32_e32 v198, v249, v194
	v_max_f32_e32 v199, v246, v195
	v_sub_f32_e32 v196, v249, v198
	v_sub_f32_e32 v197, v246, v199
	v_mul_f32_e32 v196, 0x3e0293ee, v196
	v_mul_f32_e32 v197, 0x3e0293ee, v197
	v_exp_f32_e32 v196, v196
	v_exp_f32_e32 v197, v197
	s_cmp_eq_u64 vcc, exec
	s_cselect_b64 s[8:9], -1, 0
	v_cndmask_b32_e64 v236, v196, 1.0, s[8:9]
	v_cndmask_b32_e64 v240, v197, 1.0, s[8:9]
	v_cndmask_b32_e64 v249, v198, v249, s[8:9]
	v_cndmask_b32_e64 v246, v199, v246, s[8:9]
	s_cbranch_scc1 .Lat_y_noresc
; __device__ __forceinline__ int crow(int r, int hi) { return (r & 3) + 8 * (r >> 2) + 4 * hi; }
; __device__ __forceinline__ int crow(int r, int hi) { return (r & 3) + 8 * (r >> 2) + 4 * hi; }
; __device__ __forceinline__ void attn_body256(const bf16_t* __restrict__ Qb, const bf16_t* __restrict__ Kh, const bf16_t* __restrict__ Vh,
;                                              bf16_t* Ob, int seq, unsigned char* lds, float lam, int MODE, bf16_t* Ab, const float* wsub) {
;     ...
;     if (__any(alpha < 1.f)) { if (hi == 0) al_l[r32] = alpha; asm volatile("s_waitcnt lgkmcnt(0)" ::: "memory");
; #pragma unroll
;       for (int r = 0; r < 16; ++r) { const float a = al_l[crow(r, hi)];
; #pragma unroll
;         for (int d = 0; d < 8; ++d) o[d][r] *= a; } }
	v_pk_mul_f32 v[2:3], v[2:3], v[236:237] op_sel_hi:[1,0]
	v_pk_mul_f32 v[4:5], v[4:5], v[236:237] op_sel_hi:[1,0]
	v_pk_mul_f32 v[6:7], v[6:7], v[240:241] op_sel_hi:[1,0]
	v_pk_mul_f32 v[8:9], v[8:9], v[240:241] op_sel_hi:[1,0]
	v_pk_mul_f32 v[10:11], v[10:11], v[236:237] op_sel_hi:[1,0]
	v_pk_mul_f32 v[12:13], v[12:13], v[236:237] op_sel_hi:[1,0]
	v_pk_mul_f32 v[14:15], v[14:15], v[240:241] op_sel_hi:[1,0]
	v_pk_mul_f32 v[16:17], v[16:17], v[240:241] op_sel_hi:[1,0]
	v_pk_mul_f32 v[114:115], v[114:115], v[236:237] op_sel_hi:[1,0]
	v_pk_mul_f32 v[116:117], v[116:117], v[236:237] op_sel_hi:[1,0]
	v_pk_mul_f32 v[118:119], v[118:119], v[240:241] op_sel_hi:[1,0]
	v_pk_mul_f32 v[120:121], v[120:121], v[240:241] op_sel_hi:[1,0]
	v_pk_mul_f32 v[122:123], v[122:123], v[236:237] op_sel_hi:[1,0]
	v_pk_mul_f32 v[124:125], v[124:125], v[236:237] op_sel_hi:[1,0]
	v_pk_mul_f32 v[126:127], v[126:127], v[240:241] op_sel_hi:[1,0]
	v_pk_mul_f32 v[128:129], v[128:129], v[240:241] op_sel_hi:[1,0]
	v_pk_mul_f32 v[98:99], v[98:99], v[236:237] op_sel_hi:[1,0]
	v_pk_mul_f32 v[100:101], v[100:101], v[236:237] op_sel_hi:[1,0]
	v_pk_mul_f32 v[102:103], v[102:103], v[240:241] op_sel_hi:[1,0]
	v_pk_mul_f32 v[104:105], v[104:105], v[240:241] op_sel_hi:[1,0]
	v_pk_mul_f32 v[106:107], v[106:107], v[236:237] op_sel_hi:[1,0]
	v_pk_mul_f32 v[108:109], v[108:109], v[236:237] op_sel_hi:[1,0]
	v_pk_mul_f32 v[110:111], v[110:111], v[240:241] op_sel_hi:[1,0]
	v_pk_mul_f32 v[112:113], v[112:113], v[240:241] op_sel_hi:[1,0]
	v_pk_mul_f32 v[82:83], v[82:83], v[236:237] op_sel_hi:[1,0]
	v_pk_mul_f32 v[84:85], v[84:85], v[236:237] op_sel_hi:[1,0]
	v_pk_mul_f32 v[86:87], v[86:87], v[240:241] op_sel_hi:[1,0]
	v_pk_mul_f32 v[88:89], v[88:89], v[240:241] op_sel_hi:[1,0]
	v_pk_mul_f32 v[90:91], v[90:91], v[236:237] op_sel_hi:[1,0]
	v_pk_mul_f32 v[92:93], v[92:93], v[236:237] op_sel_hi:[1,0]
	v_pk_mul_f32 v[94:95], v[94:95], v[240:241] op_sel_hi:[1,0]
	v_pk_mul_f32 v[96:97], v[96:97], v[240:241] op_sel_hi:[1,0]
	v_pk_mul_f32 v[66:67], v[66:67], v[236:237] op_sel_hi:[1,0]
	v_pk_mul_f32 v[68:69], v[68:69], v[236:237] op_sel_hi:[1,0]
	v_pk_mul_f32 v[70:71], v[70:71], v[240:241] op_sel_hi:[1,0]
	v_pk_mul_f32 v[72:73], v[72:73], v[240:241] op_sel_hi:[1,0]
	v_pk_mul_f32 v[74:75], v[74:75], v[236:237] op_sel_hi:[1,0]
	v_pk_mul_f32 v[76:77], v[76:77], v[236:237] op_sel_hi:[1,0]
	v_pk_mul_f32 v[78:79], v[78:79], v[240:241] op_sel_hi:[1,0]
	v_pk_mul_f32 v[80:81], v[80:81], v[240:241] op_sel_hi:[1,0]
	v_pk_mul_f32 v[50:51], v[50:51], v[236:237] op_sel_hi:[1,0]
	v_pk_mul_f32 v[52:53], v[52:53], v[236:237] op_sel_hi:[1,0]
	v_pk_mul_f32 v[54:55], v[54:55], v[240:241] op_sel_hi:[1,0]
	v_pk_mul_f32 v[56:57], v[56:57], v[240:241] op_sel_hi:[1,0]
	v_pk_mul_f32 v[58:59], v[58:59], v[236:237] op_sel_hi:[1,0]
	v_pk_mul_f32 v[60:61], v[60:61], v[236:237] op_sel_hi:[1,0]
	v_pk_mul_f32 v[62:63], v[62:63], v[240:241] op_sel_hi:[1,0]
	v_pk_mul_f32 v[64:65], v[64:65], v[240:241] op_sel_hi:[1,0]
	v_pk_mul_f32 v[34:35], v[34:35], v[236:237] op_sel_hi:[1,0]
	v_pk_mul_f32 v[36:37], v[36:37], v[236:237] op_sel_hi:[1,0]
	v_pk_mul_f32 v[38:39], v[38:39], v[240:241] op_sel_hi:[1,0]
	v_pk_mul_f32 v[40:41], v[40:41], v[240:241] op_sel_hi:[1,0]
	v_pk_mul_f32 v[42:43], v[42:43], v[236:237] op_sel_hi:[1,0]
	v_pk_mul_f32 v[44:45], v[44:45], v[236:237] op_sel_hi:[1,0]
	v_pk_mul_f32 v[46:47], v[46:47], v[240:241] op_sel_hi:[1,0]
	v_pk_mul_f32 v[48:49], v[48:49], v[240:241] op_sel_hi:[1,0]
	v_pk_mul_f32 v[18:19], v[18:19], v[236:237] op_sel_hi:[1,0]
	v_pk_mul_f32 v[20:21], v[20:21], v[236:237] op_sel_hi:[1,0]
	v_pk_mul_f32 v[22:23], v[22:23], v[240:241] op_sel_hi:[1,0]
	v_pk_mul_f32 v[24:25], v[24:25], v[240:241] op_sel_hi:[1,0]
	v_pk_mul_f32 v[26:27], v[26:27], v[236:237] op_sel_hi:[1,0]
	v_pk_mul_f32 v[28:29], v[28:29], v[236:237] op_sel_hi:[1,0]
	v_pk_mul_f32 v[30:31], v[30:31], v[240:241] op_sel_hi:[1,0]
	v_pk_mul_f32 v[32:33], v[32:33], v[240:241] op_sel_hi:[1,0]

; __device__ __forceinline__ unsigned xb_add(unsigned* p, unsigned v) { return __hip_atomic_fetch_add(p, v, __ATOMIC_RELAXED, __HIP_MEMORY_SCOPE_AGENT); }
; __device__ __forceinline__ void xcd_barrier(const XcdBarrier& b) {
;     asm volatile("s_waitcnt vmcnt(0)" ::: "memory");
;     __syncthreads();
;     if (threadIdx.x == 0) {
;         unsigned* bar = b.bar;
;         __builtin_amdgcn_s_waitcnt(0);
;         unsigned nloc = b.st[0], nx = b.st[1];
;         if (nloc == 0u) { xcd_barrier_complete(bar, b.x, nloc, nx); b.st[0] = nloc; b.st[1] = nx; }
;         const unsigned old = xb_add(&bar[XB_XSUB(b.x)], 1u);
;         const unsigned gen = old / nloc;
;         if (old + 1u == (gen + 1u) * nloc) {
.LBB0_684:
	v_mov_b64_e32 v[210:211], 0x3ff
	v_mov_b64_e32 v[212:213], 0x400
	v_mov_b32_e32 v244, 0x3727c5ac
	v_mov_b32_e32 v245, 0x41b17218
	v_mov_b32_e32 v239, 1
	v_mov_b64_e32 v[242:243], 0x1600
	s_getreg_b32 s2, hwreg(HW_REG_XCC_ID, 0, 4)
	s_waitcnt vmcnt(0)
	s_barrier
	s_mov_b64 s[0:1], exec
	v_readlane_b32 s6, v252, 0
	v_readlane_b32 s7, v252, 1
	s_and_b64 s[6:7], s[0:1], s[6:7]
	s_mov_b64 exec, s[6:7]
	s_cbranch_execz .LBB0_736
	v_readlane_b32 s6, v254, 43
	s_waitcnt vmcnt(0) expcnt(0) lgkmcnt(0)
	s_and_b32 s2, s2, 15
	v_mov_b32_e32 v0, s6
	ds_read_b32 v3, v0
	v_readlane_b32 s6, v254, 44
	s_waitcnt lgkmcnt(0)
	v_cmp_ne_u32_e32 vcc, 0, v3
	v_mov_b32_e32 v0, s6
	ds_read_b32 v2, v0
	s_cbranch_vccnz .LBB0_700
	s_mov_b32 s12, 1
	s_branch .LBB0_688
